# speedup vs baseline: 1.0553x; 1.0005x over previous
; __device__ __forceinline__ unsigned xb_add(unsigned* p, unsigned v) { return __hip_atomic_fetch_add(p, v, __ATOMIC_RELAXED, __HIP_MEMORY_SCOPE_AGENT); }
; __device__ __forceinline__ void xcd_barrier(const XcdBarrier& b) {
;     asm volatile("s_waitcnt vmcnt(0)" ::: "memory");
;     __syncthreads();
;     if (threadIdx.x == 0) {
;         unsigned* bar = b.bar;
;         __builtin_amdgcn_s_waitcnt(0);
;         unsigned nloc = b.st[0], nx = b.st[1];
;         if (nloc == 0u) { xcd_barrier_complete(bar, b.x, nloc, nx); b.st[0] = nloc; b.st[1] = nx; }
;         const unsigned old = xb_add(&bar[XB_XSUB(b.x)], 1u);
.LBB0_1182:
	s_waitcnt vmcnt(0)
	s_waitcnt vmcnt(0)
	s_barrier
	s_mov_b64 s[0:1], exec
	v_readlane_b32 s4, v251, 2
	v_readlane_b32 s5, v251, 3
	s_and_b64 s[4:5], s[0:1], s[4:5]
	s_mov_b64 exec, s[4:5]
	s_branch .LBB0_1230
	v_readlane_b32 s4, v254, 16
	s_waitcnt vmcnt(0) expcnt(0) lgkmcnt(0)
	s_nop 0
	v_mov_b32_e32 v0, s4
	ds_read_b32 v2, v0
	v_readlane_b32 s4, v254, 17
	s_waitcnt lgkmcnt(0)
	v_cmp_ne_u32_e32 vcc, 0, v2
	v_mov_b32_e32 v0, s4
	ds_read_b32 v0, v0
	s_cbranch_vccnz .LBB0_1198
	s_mov_b32 s4, 1
	s_branch .LBB0_1186
